# indexer score loop: relu fold, first-trip vmcnt ladder hoisted out of loop, tile staged via LDS and stored as 4 dwordx4 instead of 16 dword
# speedup vs baseline: 1.0025x; 1.0025x over previous
.LBB0_1116:
	v_writelane_b32 v251, s94, 50
	s_add_u32 s0, s90, 0x232a0800
	s_mul_i32 s7, s38, 0x82000
	v_writelane_b32 v251, s95, 51
	v_writelane_b32 v251, s0, 52
	s_addc_u32 s0, s91, 0
	v_writelane_b32 v251, s0, 54
	s_ashr_i32 s0, s38, 31
	v_writelane_b32 v251, s0, 56
	s_mul_hi_i32 s6, s38, 0x82000
	s_add_u32 s0, s90, s7
	s_addc_u32 s1, s91, s6
	s_add_u32 s4, s0, 0x23ab6800
	s_addc_u32 s5, s1, 0
	s_add_u32 s0, s90, 0x23ab67f8
	s_addc_u32 s1, s91, 0
	v_writelane_b32 v251, s0, 48
	s_waitcnt vmcnt(1)
	v_lshrrev_b32_e32 v1, 5, v192
	v_mov_b32_e32 v197, 0
	v_writelane_b32 v251, s1, 49
	s_add_u32 s0, s90, 0x22aa0800
	v_writelane_b32 v251, s0, 57
	s_addc_u32 s0, s91, 0
	v_lshlrev_b32_e32 v196, 4, v1
	v_writelane_b32 v251, s0, 59
	v_lshl_add_u64 v[2:3], s[90:91], 0, v[196:197]
	s_mov_b64 s[0:1], 0x20a80800
	s_add_u32 s62, s90, 0x236b0800
	v_and_b32_e32 v194, 31, v96
	v_lshl_add_u64 v[198:199], v[2:3], 0, s[0:1]
	s_addc_u32 s63, s91, 0
	s_lshl_b32 s0, s92, 5
	v_or_b32_e32 v2, s0, v194
	v_ashrrev_i32_e32 v3, 31, v2
	v_lshlrev_b32_e32 v200, 2, v1
	s_mov_b32 s65, s0
	v_lshlrev_b64 v[208:209], 7, v[2:3]
	s_movk_i32 s0, 0x4100
	v_mov_b64_e32 v[2:3], s[4:5]
	v_mad_u64_u32 v[2:3], s[0:1], v200, s0, v[2:3]
	s_cmp_lt_i32 s92, 32
	s_cselect_b64 s[0:1], -1, 0
	v_writelane_b32 v251, s0, 46
	s_mul_i32 s9, s92, 0x4100
	v_lshlrev_b32_e32 v196, 2, v194
	v_writelane_b32 v251, s1, 47
	s_mul_hi_i32 s8, s92, 0x4100
	s_add_u32 s0, s4, s9
	v_lshl_add_u64 v[210:211], v[2:3], 0, v[196:197]
	s_addc_u32 s1, s5, s8
	v_lshlrev_b32_e32 v196, 2, v192
	v_lshl_add_u64 v[212:213], s[0:1], 0, v[196:197]
	s_lshl_b32 s0, s92, 10
	s_add_u32 s94, s90, 0x33eb6800
	v_writelane_b32 v251, s4, 61
	s_addc_u32 s95, s91, 0
	s_add_i32 s93, s0, 0
	v_writelane_b32 v251, s5, 62
	s_add_u32 s0, s90, 0x20260800
	v_writelane_b32 v251, s0, 63
	s_addc_u32 s0, s91, 0
	v_lshlrev_b64 v[2:3], v192, -1
	v_writelane_b32 v250, s0, 0
	s_add_u32 s0, s90, 0x1fa40800
	v_writelane_b32 v250, s0, 1
	s_addc_u32 s0, s91, 0
	v_writelane_b32 v250, s0, 2
	s_add_u32 s0, s90, 0x17980800
	v_writelane_b32 v250, s0, 3
	s_addc_u32 s0, s91, 0
	v_writelane_b32 v250, s0, 4
	s_add_u32 s0, s90, 0x15900800
	v_writelane_b32 v250, s0, 5
	s_addc_u32 s0, s91, 0
	v_writelane_b32 v250, s0, 6
	s_add_u32 s0, s7, s9
	s_addc_u32 s1, s6, s8
	s_add_u32 s0, s90, s0
	s_addc_u32 s1, s91, s1
	s_add_u32 s0, s0, 0x23ab6800
	v_ashrrev_i32_e32 v97, 31, v96
	v_writelane_b32 v250, s0, 7
	s_addc_u32 s0, s1, 0
	v_lshlrev_b32_e32 v0, 3, v1
	v_not_b32_e32 v217, v3
	v_not_b32_e32 v216, v2
	v_writelane_b32 v250, s0, 9
	v_lshlrev_b64 v[2:3], 5, v[96:97]
	s_mov_b64 s[0:1], 0xc010
	s_mov_b32 s61, 0
	v_cmp_eq_u32_e64 s[2:3], 0, v96
	v_or_b32_e32 v229, 0x1000, v192
	v_mov_b32_e32 v195, v197
	v_or_b32_e32 v202, 24, v200
	v_mov_b32_e32 v203, v197
	v_or_b32_e32 v204, 16, v200
	v_mov_b32_e32 v205, v197
	v_or_b32_e32 v206, 8, v200
	v_mov_b32_e32 v207, v197
	v_mov_b32_e32 v201, v197
	v_mov_b32_e32 v193, v197
	v_lshl_add_u64 v[214:215], s[4:5], 0, v[196:197]
	v_cmp_eq_u32_e64 s[4:5], 0, v192
	v_lshlrev_b32_e32 v230, 6, v192
	v_lshl_add_u32 v231, v192, 3, s93
	v_lshlrev_b64 v[218:219], 3, v[96:97]
	v_xor_b32_e32 v232, 0x1e0, v192
	v_or_b32_e32 v221, 64, v192
	v_mov_b32_e32 v220, v192
	v_or_b32_e32 v233, 0x100, v194
	v_lshl_add_u64 v[222:223], v[2:3], 0, s[0:1]
	v_lshlrev_b32_e32 v224, 1, v0
	s_movk_i32 s0, 0x4000
	v_mov_b32_e32 v234, 0xff800000
	v_mov_b32_e32 v235, 0x4100
	v_lshrrev_b32_e32 v252, 5, v192
	v_and_b32_e32 v253, 31, v192
	v_mul_u32_u24_e32 v252, 0x240, v252
	v_lshl_add_u32 v252, v253, 2, v252
	s_mul_i32 s100, s92, 0x1200
	s_add_i32 s100, s100, 0x10000
	v_add_u32_e32 v252, s100, v252
	v_lshrrev_b32_e32 v253, 3, v192
	v_and_b32_e32 v254, 7, v192
	v_mul_u32_u24_e32 v255, 0x90, v253
	v_lshl_add_u32 v255, v254, 4, v255
	v_mul_u32_u24_e32 v253, 0x4100, v253
	v_lshl_add_u32 v254, v254, 4, v253
	v_add_u32_e32 v253, s100, v255
	v_readlane_b32 s98, v251, 61
	v_readlane_b32 s99, v251, 62
	s_branch .LBB0_1119

.LBB0_1133:
	s_add_i32 s14, s14, 64
	s_and_b64 s[6:7], s[6:7], exec
	s_cselect_b32 s60, 0x1020, s14
	s_lshr_b32 s12, s60, 5
	s_cmp_ge_i32 s92, s12
	s_cbranch_scc1 .LBB0_1138
	v_lshl_add_u64 v[0:1], s[66:67], 0, v[194:195]
	v_lshlrev_b64 v[0:1], 9, v[0:1]
	v_lshl_add_u64 v[0:1], v[198:199], 0, v[0:1]
	global_load_dwordx4 v[32:35], v[0:1], off
	global_load_dwordx4 v[36:39], v[0:1], off offset:32
	global_load_dwordx4 v[40:43], v[0:1], off offset:64
	global_load_dwordx4 v[44:47], v[0:1], off offset:96
	global_load_dwordx4 v[48:51], v[0:1], off offset:128
	global_load_dwordx4 v[52:55], v[0:1], off offset:160
	global_load_dwordx4 v[56:59], v[0:1], off offset:192
	global_load_dwordx4 v[60:63], v[0:1], off offset:224
	global_load_dwordx4 v[64:67], v[0:1], off offset:256
	global_load_dwordx4 v[68:71], v[0:1], off offset:288
	global_load_dwordx4 v[72:75], v[0:1], off offset:320
	global_load_dwordx4 v[76:79], v[0:1], off offset:352
	global_load_dwordx4 v[80:83], v[0:1], off offset:384
	global_load_dwordx4 v[84:87], v[0:1], off offset:416
	global_load_dwordx4 v[88:91], v[0:1], off offset:448
	global_load_dwordx4 v[92:95], v[0:1], off offset:480
	v_lshl_add_u64 v[0:1], s[66:67], 0, v[202:203]
	v_lshl_add_u64 v[0:1], v[0:1], 4, s[62:63]
	global_load_dwordx4 v[96:99], v[0:1], off
	global_load_dwordx4 v[100:103], v[0:1], off offset:16
	global_load_dwordx4 v[104:107], v[0:1], off offset:32
	global_load_dwordx4 v[108:111], v[0:1], off offset:48
	v_lshl_add_u64 v[0:1], s[66:67], 0, v[204:205]
	v_lshl_add_u64 v[0:1], v[0:1], 4, s[62:63]
	global_load_dwordx4 v[112:115], v[0:1], off
	global_load_dwordx4 v[116:119], v[0:1], off offset:16
	global_load_dwordx4 v[120:123], v[0:1], off offset:32
	global_load_dwordx4 v[124:127], v[0:1], off offset:48
	v_lshl_add_u64 v[0:1], s[66:67], 0, v[206:207]
	v_lshl_add_u64 v[0:1], v[0:1], 4, s[62:63]
	global_load_dwordx4 v[128:131], v[0:1], off
	global_load_dwordx4 v[132:135], v[0:1], off offset:16
	global_load_dwordx4 v[136:139], v[0:1], off offset:32
	global_load_dwordx4 v[140:143], v[0:1], off offset:48
	v_lshl_add_u64 v[0:1], s[66:67], 0, v[200:201]
	v_lshl_add_u64 v[0:1], v[0:1], 4, s[62:63]
	global_load_dwordx4 v[144:147], v[0:1], off
	global_load_dwordx4 v[148:151], v[0:1], off offset:16
	global_load_dwordx4 v[152:155], v[0:1], off offset:32
	global_load_dwordx4 v[156:159], v[0:1], off offset:48
	v_lshl_add_u64 v[0:1], s[10:11], 0, v[208:209]
	v_mov_b32_e32 v225, v197
	v_lshl_add_u64 v[0:1], v[0:1], 0, v[224:225]
	global_load_dwordx4 v[188:191], v[0:1], off
	global_load_dwordx4 v[184:187], v[0:1], off offset:32
	global_load_dwordx4 v[180:183], v[0:1], off offset:64
	global_load_dwordx4 v[176:179], v[0:1], off offset:96
	v_lshl_add_u64 v[226:227], s[10:11], 0, v[224:225]
	s_mov_b32 s6, s65
	s_mov_b32 s10, s92
	s_waitcnt vmcnt(0)
	s_branch .LBB0_1136
.LBB0_1135:
	v_mfma_f32_32x32x16_bf16 v[0:15], v[32:35], v[188:191], 0
	s_ashr_i32 s7, s6, 31
	v_mfma_f32_32x32x16_bf16 v[0:15], v[36:39], v[184:187], v[0:15]
	v_mfma_f32_32x32x16_bf16 v[0:15], v[40:43], v[180:183], v[0:15]
	v_mfma_f32_32x32x16_bf16 v[16:31], v[48:51], v[188:191], 0
	v_mfma_f32_32x32x16_bf16 v[0:15], v[44:47], v[176:179], v[0:15]
	v_mfma_f32_32x32x16_bf16 v[16:31], v[52:55], v[184:187], v[16:31]
	s_nop 10
	v_max_f32_e32 v0, 0, v0
	v_fma_f32 v242, v144, v0, 0
	v_max_f32_e32 v0, 0, v9
	v_fma_f32 v244, v116, v0, 0
	v_mfma_f32_32x32x16_bf16 v[16:31], v[56:59], v[180:183], v[16:31]
	v_max_f32_e32 v0, 0, v10
	v_fma_f32 v243, v120, v0, 0
	v_max_f32_e32 v0, 0, v11
	v_fma_f32 v246, v124, v0, 0
	v_max_f32_e32 v0, 0, v12
	v_mfma_f32_32x32x16_bf16 v[16:31], v[60:63], v[176:179], v[16:31]
	v_fma_f32 v245, v96, v0, 0
	v_max_f32_e32 v0, 0, v13
	v_fma_f32 v249, v100, v0, 0
	v_max_f32_e32 v0, 0, v14
	v_fma_f32 v248, v104, v0, 0
	v_max_f32_e32 v0, 0, v15
	v_fma_f32 v247, v108, v0, 0
	s_nop 1
	s_nop 2
	v_max_f32_e32 v0, 0, v16
	v_max_f32_e32 v1, 0, v1
	v_fmac_f32_e32 v242, v145, v0
	v_fma_f32 v241, v148, v1, 0
	v_max_f32_e32 v0, 0, v17
	v_max_f32_e32 v2, 0, v2
	v_fmac_f32_e32 v241, v149, v0
	v_fma_f32 v240, v152, v2, 0
	v_max_f32_e32 v0, 0, v18
	v_max_f32_e32 v3, 0, v3
	v_fmac_f32_e32 v240, v153, v0
	v_fma_f32 v239, v156, v3, 0
	v_max_f32_e32 v0, 0, v19
	v_max_f32_e32 v4, 0, v4
	v_fmac_f32_e32 v239, v157, v0
	v_fma_f32 v237, v128, v4, 0
	v_max_f32_e32 v0, 0, v20
	v_max_f32_e32 v5, 0, v5
	v_fmac_f32_e32 v237, v129, v0
	v_fma_f32 v236, v132, v5, 0
	v_max_f32_e32 v0, 0, v21
	v_max_f32_e32 v6, 0, v6
	v_fmac_f32_e32 v236, v133, v0
	v_fma_f32 v225, v136, v6, 0
	v_max_f32_e32 v0, 0, v22
	v_max_f32_e32 v7, 0, v7
	v_fmac_f32_e32 v225, v137, v0
	v_fma_f32 v196, v140, v7, 0
	v_max_f32_e32 v0, 0, v23
	v_max_f32_e32 v8, 0, v8
	v_fmac_f32_e32 v196, v141, v0
	v_fma_f32 v238, v112, v8, 0
	v_max_f32_e32 v0, 0, v24
	v_fmac_f32_e32 v238, v113, v0
	v_mfma_f32_32x32x16_bf16 v[0:15], v[64:67], v[188:191], 0
	v_max_f32_e32 v16, 0, v25
	v_fmac_f32_e32 v244, v117, v16
	v_max_f32_e32 v16, 0, v26
	v_fmac_f32_e32 v243, v121, v16
	v_mfma_f32_32x32x16_bf16 v[0:15], v[68:71], v[184:187], v[0:15]
	v_max_f32_e32 v16, 0, v27
	v_fmac_f32_e32 v246, v125, v16
	v_max_f32_e32 v16, 0, v28
	v_fmac_f32_e32 v245, v97, v16
	v_max_f32_e32 v16, 0, v29
	v_mfma_f32_32x32x16_bf16 v[0:15], v[72:75], v[180:183], v[0:15]
	v_fmac_f32_e32 v249, v101, v16
	v_max_f32_e32 v16, 0, v30
	v_fmac_f32_e32 v248, v105, v16
	v_max_f32_e32 v16, 0, v31
	v_fmac_f32_e32 v247, v109, v16
	v_mfma_f32_32x32x16_bf16 v[0:15], v[76:79], v[176:179], v[0:15]
	v_mfma_f32_32x32x16_bf16 v[16:31], v[80:83], v[188:191], 0
	s_nop 10
	v_max_f32_e32 v0, 0, v0
	v_fmac_f32_e32 v242, v146, v0
	v_max_f32_e32 v0, 0, v1
	v_fmac_f32_e32 v241, v150, v0
	v_max_f32_e32 v0, 0, v2
	v_fmac_f32_e32 v240, v154, v0
	v_max_f32_e32 v0, 0, v3
	v_fmac_f32_e32 v239, v158, v0
	v_mfma_f32_32x32x16_bf16 v[16:31], v[84:87], v[184:187], v[16:31]
	v_max_f32_e32 v0, 0, v4
	v_fmac_f32_e32 v237, v130, v0
	v_max_f32_e32 v0, 0, v5
	v_fmac_f32_e32 v236, v134, v0
	v_max_f32_e32 v0, 0, v6
	v_fmac_f32_e32 v225, v138, v0
	v_max_f32_e32 v0, 0, v7
	v_fmac_f32_e32 v196, v142, v0
	v_mfma_f32_32x32x16_bf16 v[16:31], v[88:91], v[180:183], v[16:31]
	v_max_f32_e32 v0, 0, v8
	v_fmac_f32_e32 v238, v114, v0
	v_max_f32_e32 v0, 0, v9
	v_fmac_f32_e32 v244, v118, v0
	v_max_f32_e32 v0, 0, v10
	v_fmac_f32_e32 v243, v122, v0
	v_max_f32_e32 v0, 0, v11
	v_fmac_f32_e32 v246, v126, v0
	v_mfma_f32_32x32x16_bf16 v[16:31], v[92:95], v[176:179], v[16:31]
	v_max_f32_e32 v0, 0, v12
	v_fmac_f32_e32 v245, v98, v0
	v_max_f32_e32 v0, 0, v13
	v_fmac_f32_e32 v249, v102, v0
	v_max_f32_e32 v0, 0, v14
	v_fmac_f32_e32 v248, v106, v0
	v_max_f32_e32 v0, 0, v15
	v_fmac_f32_e32 v247, v110, v0
	s_nop 0
	s_nop 2
	v_max_f32_e32 v0, 0, v16
	v_fmac_f32_e32 v242, v147, v0
	v_max_f32_e32 v0, 0, v17
	v_fmac_f32_e32 v241, v151, v0
	v_max_f32_e32 v0, 0, v18
	v_fmac_f32_e32 v240, v155, v0
	v_max_f32_e32 v0, 0, v19
	v_fmac_f32_e32 v239, v159, v0
	v_max_f32_e32 v0, 0, v20
	v_fmac_f32_e32 v237, v131, v0
	v_max_f32_e32 v0, 0, v21
	v_fmac_f32_e32 v236, v135, v0
	v_max_f32_e32 v0, 0, v22
	v_fmac_f32_e32 v225, v139, v0
	v_max_f32_e32 v0, 0, v23
	v_fmac_f32_e32 v196, v143, v0
	v_max_f32_e32 v0, 0, v24
	v_fmac_f32_e32 v238, v115, v0
	v_max_f32_e32 v0, 0, v25
	v_fmac_f32_e32 v244, v119, v0
	v_max_f32_e32 v0, 0, v26
	v_fmac_f32_e32 v243, v123, v0
	v_max_f32_e32 v0, 0, v27
	v_fmac_f32_e32 v246, v127, v0
	v_max_f32_e32 v0, 0, v28
	v_fmac_f32_e32 v245, v99, v0
	v_max_f32_e32 v0, 0, v29
	v_fmac_f32_e32 v249, v103, v0
	v_max_f32_e32 v0, 0, v30
	v_fmac_f32_e32 v248, v107, v0
	v_max_f32_e32 v0, 0, v31
	v_fmac_f32_e32 v247, v111, v0
	ds_write_b32 v252, v242
	ds_write_b32 v252, v241 offset:144
	ds_write_b32 v252, v240 offset:288
	ds_write_b32 v252, v239 offset:432
	ds_write_b32 v252, v237 offset:1152
	ds_write_b32 v252, v236 offset:1296
	ds_write_b32 v252, v225 offset:1440
	ds_write_b32 v252, v196 offset:1584
	ds_write_b32 v252, v238 offset:2304
	ds_write_b32 v252, v244 offset:2448
	ds_write_b32 v252, v243 offset:2592
	ds_write_b32 v252, v246 offset:2736
	ds_write_b32 v252, v245 offset:3456
	ds_write_b32 v252, v249 offset:3600
	ds_write_b32 v252, v248 offset:3744
	ds_write_b32 v252, v247 offset:3888
	s_lshl_b64 s[100:101], s[6:7], 2
	s_add_u32 s100, s100, s98
	s_addc_u32 s101, s101, s99
	s_addk_i32 s6, 0x100
	s_waitcnt lgkmcnt(0)
	ds_read_b128 v[0:3], v253
	ds_read_b128 v[4:7], v253 offset:1152
	ds_read_b128 v[8:11], v253 offset:2304
	ds_read_b128 v[12:15], v253 offset:3456
	s_waitcnt lgkmcnt(3)
	global_store_dwordx4 v254, v[0:3], s[100:101]
	s_add_u32 s100, s100, 0x20800
	s_addc_u32 s101, s101, 0
	s_waitcnt lgkmcnt(2)
	global_store_dwordx4 v254, v[4:7], s[100:101]
	s_add_u32 s100, s100, 0x20800
	s_addc_u32 s101, s101, 0
	s_waitcnt lgkmcnt(1)
	global_store_dwordx4 v254, v[8:11], s[100:101]
	s_add_u32 s100, s100, 0x20800
	s_addc_u32 s101, s101, 0
	s_waitcnt lgkmcnt(0)
	global_store_dwordx4 v254, v[12:15], s[100:101]
	s_and_b64 vcc, exec, s[8:9]
	s_waitcnt vmcnt(4)
	v_mov_b64_e32 v[178:179], v[162:163]
	v_mov_b64_e32 v[182:183], v[166:167]
	v_mov_b64_e32 v[186:187], v[170:171]
	v_mov_b64_e32 v[190:191], v[174:175]
	v_mov_b64_e32 v[176:177], v[160:161]
	v_mov_b64_e32 v[180:181], v[164:165]
	v_mov_b64_e32 v[184:185], v[168:169]
	v_mov_b64_e32 v[188:189], v[172:173]
	s_cbranch_vccnz .LBB0_1138

	.amdhsa_kernel _Z11fox_dsa_fwd2KP
		.amdhsa_group_segment_fixed_size 0
		.amdhsa_private_segment_fixed_size 0
		.amdhsa_kernarg_size 416
		.amdhsa_user_sgpr_count 2
		.amdhsa_user_sgpr_dispatch_ptr 0
		.amdhsa_user_sgpr_queue_ptr 0
		.amdhsa_user_sgpr_kernarg_segment_ptr 1
		.amdhsa_user_sgpr_dispatch_id 0
		.amdhsa_user_sgpr_kernarg_preload_length 0
		.amdhsa_user_sgpr_kernarg_preload_offset 0
		.amdhsa_user_sgpr_private_segment_size 0
		.amdhsa_uses_dynamic_stack 0
		.amdhsa_enable_private_segment 0
		.amdhsa_system_sgpr_workgroup_id_x 1
		.amdhsa_system_sgpr_workgroup_id_y 0
		.amdhsa_system_sgpr_workgroup_id_z 0
		.amdhsa_system_sgpr_workgroup_info 0
		.amdhsa_system_vgpr_workitem_id 2
		.amdhsa_next_free_vgpr 256
		.amdhsa_next_free_sgpr 102
		.amdhsa_accum_offset 256
		.amdhsa_reserve_vcc 1
		.amdhsa_float_round_mode_32 0
		.amdhsa_float_round_mode_16_64 0
		.amdhsa_float_denorm_mode_32 3
		.amdhsa_float_denorm_mode_16_64 3
		.amdhsa_dx10_clamp 1
		.amdhsa_ieee_mode 1
		.amdhsa_fp16_overflow 0
		.amdhsa_tg_split 0
		.amdhsa_exception_fp_ieee_invalid_op 0
		.amdhsa_exception_fp_denorm_src 0
		.amdhsa_exception_fp_ieee_div_zero 0
		.amdhsa_exception_fp_ieee_overflow 0
		.amdhsa_exception_fp_ieee_underflow 0
		.amdhsa_exception_fp_ieee_inexact 0
		.amdhsa_exception_int_div_zero 0
	.end_amdhsa_kernel

amdhsa.kernels:
  - .agpr_count:     0
    .args:
      - .offset:         0
        .size:           160
        .value_kind:     by_value
      - .offset:         160
        .size:           4
        .value_kind:     hidden_block_count_x
      - .offset:         164
        .size:           4
        .value_kind:     hidden_block_count_y
      - .offset:         168
        .size:           4
        .value_kind:     hidden_block_count_z
      - .offset:         172
        .size:           2
        .value_kind:     hidden_group_size_x
      - .offset:         174
        .size:           2
        .value_kind:     hidden_group_size_y
      - .offset:         176
        .size:           2
        .value_kind:     hidden_group_size_z
      - .offset:         178
        .size:           2
        .value_kind:     hidden_remainder_x
      - .offset:         180
        .size:           2
        .value_kind:     hidden_remainder_y
      - .offset:         182
        .size:           2
        .value_kind:     hidden_remainder_z
      - .offset:         200
        .size:           8
        .value_kind:     hidden_global_offset_x
      - .offset:         208
        .size:           8
        .value_kind:     hidden_global_offset_y
      - .offset:         216
        .size:           8
        .value_kind:     hidden_global_offset_z
      - .offset:         224
        .size:           2
        .value_kind:     hidden_grid_dims
      - .offset:         248
        .size:           8
        .value_kind:     hidden_multigrid_sync_arg
      - .offset:         280
        .size:           4
        .value_kind:     hidden_dynamic_lds_size
    .group_segment_fixed_size: 0
    .kernarg_segment_align: 8
    .kernarg_segment_size: 416
    .language:       OpenCL C
    .language_version:
      - 2
      - 0
    .max_flat_workgroup_size: 512
    .name:           _Z11fox_dsa_fwd2KP
    .private_segment_fixed_size: 0
    .sgpr_count:     108
    .sgpr_spill_count: 116
    .symbol:         _Z11fox_dsa_fwd2KP.kd
    .uniform_work_group_size: 1
    .uses_dynamic_stack: false
    .vgpr_count:     256
    .vgpr_spill_count: 0
    .wavefront_size: 64
